# slot table T9: w_in slots 6 full rounds (744), pre-loop slot 1 round (208)
# speedup vs baseline: 1.0116x; 1.0084x over previous
; __device__ __forceinline__ int ltid() { int t = __builtin_amdgcn_workitem_id_x(); asm volatile("" : "+v"(t)); return t; }
; __device__ void phase_convert(PP p, unsigned char* smem) {
;   float* tile = (float*)smem;
;   const int tid = ltid(), n4 = tid & 31, kl = tid >> 5;
;   const float* src; int ld, K, k0, n0; bf16_t* dst;
;   f32x4 cur[4], nxt[4];
;   int t = blockIdx.x;
;   if (t < NT_ALL) {
;     cvt_decode(p, t, src, ld, dst, K, k0, n0, n4);
; #pragma unroll
;     for (int i = 0; i < 4; ++i) cur[i] = src ? *(const f32x4*)(src + (size_t)(kl + 16 * i) * ld) : (f32x4){0.f, 0.f, 0.f, 0.f};
;   }
;   for (; t < NT_ALL; t += gridDim.x) {
.LBB0_123:
	s_mov_b32 s98, s2
	s_mov_b32 s99, 208
	s_mov_b32 s100, s60
	s_mov_b64 exec, -1
	v_writelane_b32 v154, s10, 0
	v_writelane_b32 v154, s11, 1
	v_writelane_b32 v154, s12, 2
	v_writelane_b32 v154, s13, 3
	v_writelane_b32 v154, s14, 4
	v_writelane_b32 v154, s15, 5
	v_writelane_b32 v154, s16, 6
	v_writelane_b32 v154, s17, 7
	v_writelane_b32 v154, s18, 8
	v_writelane_b32 v154, s19, 9
	v_writelane_b32 v154, s20, 10
	v_writelane_b32 v154, s21, 11
	v_writelane_b32 v154, s22, 12
	v_writelane_b32 v154, s23, 13
	v_writelane_b32 v154, s24, 14
	v_writelane_b32 v154, s25, 15
	v_readlane_b32 s4, v254, 0
	v_readlane_b32 s5, v254, 1
	v_and_b32_e32 v0, 7, v228
	v_lshrrev_b32_e32 v1, 3, v228
	s_nop 1
	s_load_dwordx2 s[8:9], s[4:5], 0xe0
	s_waitcnt lgkmcnt(0)
	s_mov_b32 s17, s98
	s_mov_b32 s18, 1
	s_branch .Lcvp_dec

; __device__ void phase_convert(PP p, unsigned char* smem) {
;     ...
;   int t = blockIdx.x;
;   if (t < NT_ALL) {
;     cvt_decode(p, t, src, ld, dst, K, k0, n0, n4);
; #pragma unroll
;     for (int i = 0; i < 4; ++i) cur[i] = src ? *(const f32x4*)(src + (size_t)(kl + 16 * i) * ld) : (f32x4){0.f, 0.f, 0.f, 0.f};
;   }
;   for (; t < NT_ALL; t += gridDim.x) {
;     const int tn = t + gridDim.x;
;     const float* src2 = nullptr; int ld2 = 0, K2, k02, n02; bf16_t* dst2;
.Lcvt_t0:
	s_mov_b32 s98, 208
	s_mov_b32 s99, 624
	s_mov_b32 s100, 48
	s_branch .Lcvt_go
.Lcvt_t1:
	s_mov_b32 s98, 624
	s_mov_b32 s99, 1008
	s_mov_b32 s100, 128
	s_branch .Lcvt_go
.Lcvt_t3:
	s_mov_b32 s98, 1008
	s_mov_b32 s99, 1752
	s_mov_b32 s100, 132
	s_branch .Lcvt_go
.Lcvt_t7:
	s_mov_b32 s98, 1752
	s_mov_b32 s99, 1880
	s_mov_b32 s100, 128
	s_branch .Lcvt_go
.Lcvt_t9:
	s_mov_b32 s98, 1880
	s_mov_b32 s99, 2296
	s_mov_b32 s100, 48
	s_branch .Lcvt_go
.Lcvt_t10:
	s_mov_b32 s98, 2296
	s_mov_b32 s99, 2680
	s_mov_b32 s100, 128
	s_branch .Lcvt_go
.Lcvt_t12:
	s_mov_b32 s98, 2680
	s_mov_b32 s99, 3096
	s_mov_b32 s100, 48
	s_branch .Lcvt_go
.Lcvt_t13:
	s_mov_b32 s98, 3096
	s_mov_b32 s99, 3480
	s_mov_b32 s100, 128
	s_branch .Lcvt_go
.Lcvt_t15:
	s_mov_b32 s98, 3480
	s_mov_b32 s99, 4224
	s_mov_b32 s100, 132
	s_branch .Lcvt_go
